# UP-GEMM SwiGLU epilogue rewritten with packed f32 ops (v_pk_mul/v_pk_add), identical arithmetic and rounding per output, ~30 pct fewer VALU issue slots
# speedup vs baseline: 1.0186x; 1.0085x over previous
.LBB0_609:
	s_add_u32 s8, s70, 0x40080
	s_addc_u32 s9, s25, 0
	s_mov_b32 m0, s65
	s_nop 0
	global_load_lds_dwordx4 v0, s[8:9]
	v_lshl_add_u32 v141, s69, 10, v136
	s_mov_b32 m0, s66
	s_nop 0
	global_load_lds_dwordx4 v133, s[8:9]
	ds_read_b32 v145, v141
	v_lshl_or_b32 v142, s68, 7, v137
	v_lshl_add_u32 v140, s34, 8, v135
	v_ashrrev_i32_e32 v143, 31, v142
	v_mov_b64_e32 v[130:131], s[6:7]
	v_lshlrev_b64 v[142:143], 1, v[142:143]
	v_mad_i64_i32 v[130:131], s[8:9], v140, s87, v[130:131]
	s_lshl_b32 s8, s87, 4
	s_mov_b32 s9, 0
	v_lshl_add_u64 v[142:143], v[130:131], 0, v[142:143]
	s_waitcnt lgkmcnt(0)
	v_mul_f32_e32 v144, 0xbfb8aa3b, v145
	v_mul_f32_e32 v146, v145, v145
	ds_read_b32 v145, v141 offset:64
	v_pk_mul_f32 v[148:149], v[122:123], v[144:145] op_sel_hi:[1,0]
	v_pk_mul_f32 v[126:127], v[122:123], v[126:127]
	v_pk_mul_f32 v[150:151], v[124:125], v[144:145] op_sel_hi:[1,0]
	v_pk_mul_f32 v[128:129], v[124:125], v[128:129]
	v_exp_f32_e32 v122, v148
	v_exp_f32_e32 v123, v149
	v_pk_mul_f32 v[126:127], v[126:127], v[146:147] op_sel_hi:[1,0]
	v_exp_f32_e32 v124, v150
	v_exp_f32_e32 v125, v151
	v_pk_mul_f32 v[128:129], v[128:129], v[146:147] op_sel_hi:[1,0]
	v_pk_mul_f32 v[148:149], v[114:115], v[144:145] op_sel_hi:[1,0]
	v_pk_mul_f32 v[118:119], v[114:115], v[118:119]
	v_pk_add_f32 v[122:123], v[122:123], 1.0 op_sel_hi:[1,0]
	v_pk_mul_f32 v[150:151], v[116:117], v[144:145] op_sel_hi:[1,0]
	v_pk_mul_f32 v[120:121], v[116:117], v[120:121]
	v_pk_add_f32 v[124:125], v[124:125], 1.0 op_sel_hi:[1,0]
	v_rcp_f32_e32 v122, v122
	v_rcp_f32_e32 v123, v123
	v_exp_f32_e32 v114, v148
	v_exp_f32_e32 v115, v149
	v_pk_mul_f32 v[118:119], v[118:119], v[146:147] op_sel_hi:[1,0]
	v_rcp_f32_e32 v124, v124
	v_rcp_f32_e32 v125, v125
	v_exp_f32_e32 v116, v150
	v_exp_f32_e32 v117, v151
	v_pk_mul_f32 v[120:121], v[120:121], v[146:147] op_sel_hi:[1,0]
	v_pk_mul_f32 v[126:127], v[126:127], v[122:123]
	v_pk_add_f32 v[114:115], v[114:115], 1.0 op_sel_hi:[1,0]
	v_pk_mul_f32 v[128:129], v[128:129], v[124:125]
	v_pk_add_f32 v[116:117], v[116:117], 1.0 op_sel_hi:[1,0]
	v_rcp_f32_e32 v114, v114
	v_rcp_f32_e32 v115, v115
	v_rcp_f32_e32 v116, v116
	v_rcp_f32_e32 v117, v117
	v_cvt_pk_bf16_f32 v122, v126, v127
	v_cvt_pk_bf16_f32 v123, v128, v129
	v_pk_mul_f32 v[118:119], v[118:119], v[114:115]
	v_pk_mul_f32 v[120:121], v[120:121], v[116:117]
	v_cvt_pk_bf16_f32 v124, v118, v119
	v_cvt_pk_bf16_f32 v125, v120, v121
	global_store_dwordx4 v[142:143], v[122:125], off
	s_waitcnt lgkmcnt(0)
	v_mul_f32_e32 v144, 0xbfb8aa3b, v145
	v_mul_f32_e32 v146, v145, v145
	ds_read_b32 v145, v141 offset:128
	v_lshl_add_u64 v[142:143], v[142:143], 0, s[8:9]
	v_pk_mul_f32 v[148:149], v[106:107], v[144:145] op_sel_hi:[1,0]
	v_pk_mul_f32 v[110:111], v[106:107], v[110:111]
	v_pk_mul_f32 v[150:151], v[108:109], v[144:145] op_sel_hi:[1,0]
	v_pk_mul_f32 v[112:113], v[108:109], v[112:113]
	v_exp_f32_e32 v106, v148
	v_exp_f32_e32 v107, v149
	v_pk_mul_f32 v[110:111], v[110:111], v[146:147] op_sel_hi:[1,0]
	v_exp_f32_e32 v108, v150
	v_exp_f32_e32 v109, v151
	v_pk_mul_f32 v[112:113], v[112:113], v[146:147] op_sel_hi:[1,0]
	v_pk_mul_f32 v[148:149], v[98:99], v[144:145] op_sel_hi:[1,0]
	v_pk_mul_f32 v[102:103], v[98:99], v[102:103]
	v_pk_add_f32 v[106:107], v[106:107], 1.0 op_sel_hi:[1,0]
	v_pk_mul_f32 v[150:151], v[100:101], v[144:145] op_sel_hi:[1,0]
	v_pk_mul_f32 v[104:105], v[100:101], v[104:105]
	v_pk_add_f32 v[108:109], v[108:109], 1.0 op_sel_hi:[1,0]
	v_rcp_f32_e32 v106, v106
	v_rcp_f32_e32 v107, v107
	v_exp_f32_e32 v98, v148
	v_exp_f32_e32 v99, v149
	v_pk_mul_f32 v[102:103], v[102:103], v[146:147] op_sel_hi:[1,0]
	v_rcp_f32_e32 v108, v108
	v_rcp_f32_e32 v109, v109
	v_exp_f32_e32 v100, v150
	v_exp_f32_e32 v101, v151
	v_pk_mul_f32 v[104:105], v[104:105], v[146:147] op_sel_hi:[1,0]
	v_pk_mul_f32 v[110:111], v[110:111], v[106:107]
	v_pk_add_f32 v[98:99], v[98:99], 1.0 op_sel_hi:[1,0]
	v_pk_mul_f32 v[112:113], v[112:113], v[108:109]
	v_pk_add_f32 v[100:101], v[100:101], 1.0 op_sel_hi:[1,0]
	v_rcp_f32_e32 v98, v98
	v_rcp_f32_e32 v99, v99
	v_rcp_f32_e32 v100, v100
	v_rcp_f32_e32 v101, v101
	v_cvt_pk_bf16_f32 v106, v110, v111
	v_cvt_pk_bf16_f32 v107, v112, v113
	v_pk_mul_f32 v[102:103], v[102:103], v[98:99]
	v_pk_mul_f32 v[104:105], v[104:105], v[100:101]
	v_cvt_pk_bf16_f32 v108, v102, v103
	v_cvt_pk_bf16_f32 v109, v104, v105
	global_store_dwordx4 v[142:143], v[106:109], off
	s_waitcnt lgkmcnt(0)
	v_mul_f32_e32 v144, 0xbfb8aa3b, v145
	v_mul_f32_e32 v146, v145, v145
	ds_read_b32 v145, v141 offset:192
	v_lshl_add_u64 v[142:143], v[142:143], 0, s[8:9]
	v_pk_mul_f32 v[148:149], v[90:91], v[144:145] op_sel_hi:[1,0]
	v_pk_mul_f32 v[94:95], v[90:91], v[94:95]
	v_pk_mul_f32 v[150:151], v[92:93], v[144:145] op_sel_hi:[1,0]
	v_pk_mul_f32 v[96:97], v[92:93], v[96:97]
	v_exp_f32_e32 v90, v148
	v_exp_f32_e32 v91, v149
	v_pk_mul_f32 v[94:95], v[94:95], v[146:147] op_sel_hi:[1,0]
	v_exp_f32_e32 v92, v150
	v_exp_f32_e32 v93, v151
	v_pk_mul_f32 v[96:97], v[96:97], v[146:147] op_sel_hi:[1,0]
	v_pk_mul_f32 v[148:149], v[82:83], v[144:145] op_sel_hi:[1,0]
	v_pk_mul_f32 v[86:87], v[82:83], v[86:87]
	v_pk_add_f32 v[90:91], v[90:91], 1.0 op_sel_hi:[1,0]
	v_pk_mul_f32 v[150:151], v[84:85], v[144:145] op_sel_hi:[1,0]
	v_pk_mul_f32 v[88:89], v[84:85], v[88:89]
	v_pk_add_f32 v[92:93], v[92:93], 1.0 op_sel_hi:[1,0]
	v_rcp_f32_e32 v90, v90
	v_rcp_f32_e32 v91, v91
	v_exp_f32_e32 v82, v148
	v_exp_f32_e32 v83, v149
	v_pk_mul_f32 v[86:87], v[86:87], v[146:147] op_sel_hi:[1,0]
	v_rcp_f32_e32 v92, v92
	v_rcp_f32_e32 v93, v93
	v_exp_f32_e32 v84, v150
	v_exp_f32_e32 v85, v151
	v_pk_mul_f32 v[88:89], v[88:89], v[146:147] op_sel_hi:[1,0]
	v_pk_mul_f32 v[94:95], v[94:95], v[90:91]
	v_pk_add_f32 v[82:83], v[82:83], 1.0 op_sel_hi:[1,0]
	v_pk_mul_f32 v[96:97], v[96:97], v[92:93]
	v_pk_add_f32 v[84:85], v[84:85], 1.0 op_sel_hi:[1,0]
	v_rcp_f32_e32 v82, v82
	v_rcp_f32_e32 v83, v83
	v_rcp_f32_e32 v84, v84
	v_rcp_f32_e32 v85, v85
	v_cvt_pk_bf16_f32 v90, v94, v95
	v_cvt_pk_bf16_f32 v91, v96, v97
	v_pk_mul_f32 v[86:87], v[86:87], v[82:83]
	v_pk_mul_f32 v[88:89], v[88:89], v[84:85]
	v_cvt_pk_bf16_f32 v92, v86, v87
	v_cvt_pk_bf16_f32 v93, v88, v89
	global_store_dwordx4 v[142:143], v[90:93], off
	s_waitcnt lgkmcnt(0)
	v_mul_f32_e32 v144, 0xbfb8aa3b, v145
	v_mul_f32_e32 v146, v145, v145
	ds_read_b32 v145, v141 offset:512
	v_lshl_add_u64 v[142:143], v[142:143], 0, s[8:9]
	s_mul_i32 s8, s87, 0x50
	v_pk_mul_f32 v[148:149], v[74:75], v[144:145] op_sel_hi:[1,0]
	v_pk_mul_f32 v[78:79], v[74:75], v[78:79]
	v_pk_mul_f32 v[150:151], v[76:77], v[144:145] op_sel_hi:[1,0]
	v_pk_mul_f32 v[80:81], v[76:77], v[80:81]
	v_exp_f32_e32 v74, v148
	v_exp_f32_e32 v75, v149
	v_pk_mul_f32 v[78:79], v[78:79], v[146:147] op_sel_hi:[1,0]
	v_exp_f32_e32 v76, v150
	v_exp_f32_e32 v77, v151
	v_pk_mul_f32 v[80:81], v[80:81], v[146:147] op_sel_hi:[1,0]
	v_pk_mul_f32 v[148:149], v[66:67], v[144:145] op_sel_hi:[1,0]
	v_pk_mul_f32 v[70:71], v[66:67], v[70:71]
	v_pk_add_f32 v[74:75], v[74:75], 1.0 op_sel_hi:[1,0]
	v_pk_mul_f32 v[150:151], v[68:69], v[144:145] op_sel_hi:[1,0]
	v_pk_mul_f32 v[72:73], v[68:69], v[72:73]
	v_pk_add_f32 v[76:77], v[76:77], 1.0 op_sel_hi:[1,0]
	v_rcp_f32_e32 v74, v74
	v_rcp_f32_e32 v75, v75
	v_exp_f32_e32 v66, v148
	v_exp_f32_e32 v67, v149
	v_pk_mul_f32 v[70:71], v[70:71], v[146:147] op_sel_hi:[1,0]
	v_rcp_f32_e32 v76, v76
	v_rcp_f32_e32 v77, v77
	v_exp_f32_e32 v68, v150
	v_exp_f32_e32 v69, v151
	v_pk_mul_f32 v[72:73], v[72:73], v[146:147] op_sel_hi:[1,0]
	v_pk_mul_f32 v[78:79], v[78:79], v[74:75]
	v_pk_add_f32 v[66:67], v[66:67], 1.0 op_sel_hi:[1,0]
	v_pk_mul_f32 v[80:81], v[80:81], v[76:77]
	v_pk_add_f32 v[68:69], v[68:69], 1.0 op_sel_hi:[1,0]
	v_rcp_f32_e32 v66, v66
	v_rcp_f32_e32 v67, v67
	v_rcp_f32_e32 v68, v68
	v_rcp_f32_e32 v69, v69
	v_cvt_pk_bf16_f32 v74, v78, v79
	v_cvt_pk_bf16_f32 v75, v80, v81
	v_pk_mul_f32 v[70:71], v[70:71], v[66:67]
	v_pk_mul_f32 v[72:73], v[72:73], v[68:69]
	v_cvt_pk_bf16_f32 v76, v70, v71
	v_cvt_pk_bf16_f32 v77, v72, v73
	global_store_dwordx4 v[142:143], v[74:77], off
	s_waitcnt lgkmcnt(0)
	v_mul_f32_e32 v144, 0xbfb8aa3b, v145
	v_mul_f32_e32 v146, v145, v145
	ds_read_b32 v145, v141 offset:576
	v_lshl_add_u64 v[142:143], v[142:143], 0, s[8:9]
	s_lshl_b32 s8, s87, 4
	v_pk_mul_f32 v[148:149], v[58:59], v[144:145] op_sel_hi:[1,0]
	v_pk_mul_f32 v[62:63], v[58:59], v[62:63]
	v_pk_mul_f32 v[150:151], v[60:61], v[144:145] op_sel_hi:[1,0]
	v_pk_mul_f32 v[64:65], v[60:61], v[64:65]
	v_exp_f32_e32 v58, v148
	v_exp_f32_e32 v59, v149
	v_pk_mul_f32 v[62:63], v[62:63], v[146:147] op_sel_hi:[1,0]
	v_exp_f32_e32 v60, v150
	v_exp_f32_e32 v61, v151
	v_pk_mul_f32 v[64:65], v[64:65], v[146:147] op_sel_hi:[1,0]
	v_pk_mul_f32 v[148:149], v[50:51], v[144:145] op_sel_hi:[1,0]
	v_pk_mul_f32 v[54:55], v[50:51], v[54:55]
	v_pk_add_f32 v[58:59], v[58:59], 1.0 op_sel_hi:[1,0]
	v_pk_mul_f32 v[150:151], v[52:53], v[144:145] op_sel_hi:[1,0]
	v_pk_mul_f32 v[56:57], v[52:53], v[56:57]
	v_pk_add_f32 v[60:61], v[60:61], 1.0 op_sel_hi:[1,0]
	v_rcp_f32_e32 v58, v58
	v_rcp_f32_e32 v59, v59
	v_exp_f32_e32 v50, v148
	v_exp_f32_e32 v51, v149
	v_pk_mul_f32 v[54:55], v[54:55], v[146:147] op_sel_hi:[1,0]
	v_rcp_f32_e32 v60, v60
	v_rcp_f32_e32 v61, v61
	v_exp_f32_e32 v52, v150
	v_exp_f32_e32 v53, v151
	v_pk_mul_f32 v[56:57], v[56:57], v[146:147] op_sel_hi:[1,0]
	v_pk_mul_f32 v[62:63], v[62:63], v[58:59]
	v_pk_add_f32 v[50:51], v[50:51], 1.0 op_sel_hi:[1,0]
	v_pk_mul_f32 v[64:65], v[64:65], v[60:61]
	v_pk_add_f32 v[52:53], v[52:53], 1.0 op_sel_hi:[1,0]
	v_rcp_f32_e32 v50, v50
	v_rcp_f32_e32 v51, v51
	v_rcp_f32_e32 v52, v52
	v_rcp_f32_e32 v53, v53
	v_cvt_pk_bf16_f32 v58, v62, v63
	v_cvt_pk_bf16_f32 v59, v64, v65
	v_pk_mul_f32 v[54:55], v[54:55], v[50:51]
	v_pk_mul_f32 v[56:57], v[56:57], v[52:53]
	v_cvt_pk_bf16_f32 v60, v54, v55
	v_cvt_pk_bf16_f32 v61, v56, v57
	global_store_dwordx4 v[142:143], v[58:61], off
	s_waitcnt lgkmcnt(0)
	v_mul_f32_e32 v144, 0xbfb8aa3b, v145
	v_mul_f32_e32 v146, v145, v145
	ds_read_b32 v145, v141 offset:640
	v_lshl_add_u64 v[142:143], v[142:143], 0, s[8:9]
	v_pk_mul_f32 v[148:149], v[42:43], v[144:145] op_sel_hi:[1,0]
	v_pk_mul_f32 v[46:47], v[42:43], v[46:47]
	v_pk_mul_f32 v[150:151], v[44:45], v[144:145] op_sel_hi:[1,0]
	v_pk_mul_f32 v[48:49], v[44:45], v[48:49]
	v_exp_f32_e32 v42, v148
	v_exp_f32_e32 v43, v149
	v_pk_mul_f32 v[46:47], v[46:47], v[146:147] op_sel_hi:[1,0]
	v_exp_f32_e32 v44, v150
	v_exp_f32_e32 v45, v151
	v_pk_mul_f32 v[48:49], v[48:49], v[146:147] op_sel_hi:[1,0]
	v_pk_mul_f32 v[148:149], v[34:35], v[144:145] op_sel_hi:[1,0]
	v_pk_mul_f32 v[38:39], v[34:35], v[38:39]
	v_pk_add_f32 v[42:43], v[42:43], 1.0 op_sel_hi:[1,0]
	v_pk_mul_f32 v[150:151], v[36:37], v[144:145] op_sel_hi:[1,0]
	v_pk_mul_f32 v[40:41], v[36:37], v[40:41]
	v_pk_add_f32 v[44:45], v[44:45], 1.0 op_sel_hi:[1,0]
	v_rcp_f32_e32 v42, v42
	v_rcp_f32_e32 v43, v43
	v_exp_f32_e32 v34, v148
	v_exp_f32_e32 v35, v149
	v_pk_mul_f32 v[38:39], v[38:39], v[146:147] op_sel_hi:[1,0]
	v_rcp_f32_e32 v44, v44
	v_rcp_f32_e32 v45, v45
	v_exp_f32_e32 v36, v150
	v_exp_f32_e32 v37, v151
	v_pk_mul_f32 v[40:41], v[40:41], v[146:147] op_sel_hi:[1,0]
	v_pk_mul_f32 v[46:47], v[46:47], v[42:43]
	v_pk_add_f32 v[34:35], v[34:35], 1.0 op_sel_hi:[1,0]
	v_pk_mul_f32 v[48:49], v[48:49], v[44:45]
	v_pk_add_f32 v[36:37], v[36:37], 1.0 op_sel_hi:[1,0]
	v_rcp_f32_e32 v34, v34
	v_rcp_f32_e32 v35, v35
	v_rcp_f32_e32 v36, v36
	v_rcp_f32_e32 v37, v37
	v_cvt_pk_bf16_f32 v42, v46, v47
	v_cvt_pk_bf16_f32 v43, v48, v49
	v_pk_mul_f32 v[38:39], v[38:39], v[34:35]
	v_pk_mul_f32 v[40:41], v[40:41], v[36:37]
	v_cvt_pk_bf16_f32 v44, v38, v39
	v_cvt_pk_bf16_f32 v45, v40, v41
	global_store_dwordx4 v[142:143], v[42:45], off
	s_waitcnt lgkmcnt(0)
	v_mul_f32_e32 v144, 0xbfb8aa3b, v145
	v_mul_f32_e32 v146, v145, v145
	ds_read_b32 v145, v141 offset:704
	v_lshl_add_u64 v[142:143], v[142:143], 0, s[8:9]
	v_pk_mul_f32 v[148:149], v[26:27], v[144:145] op_sel_hi:[1,0]
	v_pk_mul_f32 v[30:31], v[26:27], v[30:31]
	v_pk_mul_f32 v[150:151], v[28:29], v[144:145] op_sel_hi:[1,0]
	v_pk_mul_f32 v[32:33], v[28:29], v[32:33]
	v_exp_f32_e32 v26, v148
	v_exp_f32_e32 v27, v149
	v_pk_mul_f32 v[30:31], v[30:31], v[146:147] op_sel_hi:[1,0]
	v_exp_f32_e32 v28, v150
	v_exp_f32_e32 v29, v151
	v_pk_mul_f32 v[32:33], v[32:33], v[146:147] op_sel_hi:[1,0]
	v_pk_mul_f32 v[148:149], v[18:19], v[144:145] op_sel_hi:[1,0]
	v_pk_mul_f32 v[22:23], v[18:19], v[22:23]
	v_pk_add_f32 v[26:27], v[26:27], 1.0 op_sel_hi:[1,0]
	v_pk_mul_f32 v[150:151], v[20:21], v[144:145] op_sel_hi:[1,0]
	v_pk_mul_f32 v[24:25], v[20:21], v[24:25]
	v_pk_add_f32 v[28:29], v[28:29], 1.0 op_sel_hi:[1,0]
	v_rcp_f32_e32 v26, v26
	v_rcp_f32_e32 v27, v27
	v_exp_f32_e32 v18, v148
	v_exp_f32_e32 v19, v149
	v_pk_mul_f32 v[22:23], v[22:23], v[146:147] op_sel_hi:[1,0]
	v_rcp_f32_e32 v28, v28
	v_rcp_f32_e32 v29, v29
	v_exp_f32_e32 v20, v150
	v_exp_f32_e32 v21, v151
	v_pk_mul_f32 v[24:25], v[24:25], v[146:147] op_sel_hi:[1,0]
	v_pk_mul_f32 v[30:31], v[30:31], v[26:27]
	v_pk_add_f32 v[18:19], v[18:19], 1.0 op_sel_hi:[1,0]
	v_pk_mul_f32 v[32:33], v[32:33], v[28:29]
	v_pk_add_f32 v[20:21], v[20:21], 1.0 op_sel_hi:[1,0]
	v_rcp_f32_e32 v18, v18
	v_rcp_f32_e32 v19, v19
	v_rcp_f32_e32 v20, v20
	v_rcp_f32_e32 v21, v21
	v_cvt_pk_bf16_f32 v26, v30, v31
	v_cvt_pk_bf16_f32 v27, v32, v33
	v_pk_mul_f32 v[22:23], v[22:23], v[18:19]
	v_pk_mul_f32 v[24:25], v[24:25], v[20:21]
	v_cvt_pk_bf16_f32 v28, v22, v23
	v_cvt_pk_bf16_f32 v29, v24, v25
	global_store_dwordx4 v[142:143], v[26:29], off
	s_waitcnt lgkmcnt(0)
	v_mul_f32_e32 v144, 0xbfb8aa3b, v145
	v_mul_f32_e32 v146, v145, v145
	v_lshl_add_u64 v[142:143], v[142:143], 0, s[8:9]
	v_pk_mul_f32 v[148:149], v[10:11], v[144:145] op_sel_hi:[1,0]
	v_pk_mul_f32 v[14:15], v[10:11], v[14:15]
	v_pk_mul_f32 v[150:151], v[12:13], v[144:145] op_sel_hi:[1,0]
	v_pk_mul_f32 v[16:17], v[12:13], v[16:17]
	v_exp_f32_e32 v10, v148
	v_exp_f32_e32 v11, v149
	v_pk_mul_f32 v[14:15], v[14:15], v[146:147] op_sel_hi:[1,0]
	v_exp_f32_e32 v12, v150
	v_exp_f32_e32 v13, v151
	v_pk_mul_f32 v[16:17], v[16:17], v[146:147] op_sel_hi:[1,0]
	v_pk_mul_f32 v[148:149], v[2:3], v[144:145] op_sel_hi:[1,0]
	v_pk_mul_f32 v[6:7], v[2:3], v[6:7]
	v_pk_add_f32 v[10:11], v[10:11], 1.0 op_sel_hi:[1,0]
	v_pk_mul_f32 v[150:151], v[4:5], v[144:145] op_sel_hi:[1,0]
	v_pk_mul_f32 v[8:9], v[4:5], v[8:9]
	v_pk_add_f32 v[12:13], v[12:13], 1.0 op_sel_hi:[1,0]
	v_rcp_f32_e32 v10, v10
	v_rcp_f32_e32 v11, v11
	v_exp_f32_e32 v2, v148
	v_exp_f32_e32 v3, v149
	v_pk_mul_f32 v[6:7], v[6:7], v[146:147] op_sel_hi:[1,0]
	v_rcp_f32_e32 v12, v12
	v_rcp_f32_e32 v13, v13
	v_exp_f32_e32 v4, v150
	v_exp_f32_e32 v5, v151
	v_pk_mul_f32 v[8:9], v[8:9], v[146:147] op_sel_hi:[1,0]
	v_pk_mul_f32 v[14:15], v[14:15], v[10:11]
	v_pk_add_f32 v[2:3], v[2:3], 1.0 op_sel_hi:[1,0]
	v_pk_mul_f32 v[16:17], v[16:17], v[12:13]
	v_pk_add_f32 v[4:5], v[4:5], 1.0 op_sel_hi:[1,0]
	v_rcp_f32_e32 v2, v2
	v_rcp_f32_e32 v3, v3
	v_rcp_f32_e32 v4, v4
	v_rcp_f32_e32 v5, v5
	v_cvt_pk_bf16_f32 v10, v14, v15
	v_cvt_pk_bf16_f32 v11, v16, v17
	v_pk_mul_f32 v[6:7], v[6:7], v[2:3]
	v_pk_mul_f32 v[8:9], v[8:9], v[4:5]
	v_cvt_pk_bf16_f32 v12, v6, v7
	v_cvt_pk_bf16_f32 v13, v8, v9
	s_andn2_b64 vcc, exec, s[0:1]
	s_mov_b64 s[0:1], -1
	global_store_dwordx4 v[142:143], v[10:13], off
	s_cbranch_vccnz .LBB0_602
	s_andn2_b64 vcc, exec, s[4:5]
	v_mov_b64 v[122:123], 0
	v_mov_b64 v[124:125], 0
	v_mov_b64 v[114:115], 0
	v_mov_b64 v[116:117], 0
	v_mov_b64 v[106:107], 0
	v_mov_b64 v[108:109], 0
	v_mov_b64 v[98:99], 0
	v_mov_b64 v[100:101], 0
	v_mov_b64 v[90:91], 0
	v_mov_b64 v[92:93], 0
	v_mov_b64 v[82:83], 0
	v_mov_b64 v[84:85], 0
	v_mov_b64 v[74:75], 0
	v_mov_b64 v[76:77], 0
	v_mov_b64 v[66:67], 0
	v_mov_b64 v[68:69], 0
	v_mov_b64 v[126:127], 0
	v_mov_b64 v[128:129], 0
	v_mov_b64 v[118:119], 0
	v_mov_b64 v[120:121], 0
	v_mov_b64 v[110:111], 0
	v_mov_b64 v[112:113], 0
	v_mov_b64 v[102:103], 0
	v_mov_b64 v[104:105], 0
	v_mov_b64 v[94:95], 0
	v_mov_b64 v[96:97], 0
	v_mov_b64 v[86:87], 0
	v_mov_b64 v[88:89], 0
	v_mov_b64 v[78:79], 0
	v_mov_b64 v[80:81], 0
	v_mov_b64 v[70:71], 0
	v_mov_b64 v[72:73], 0
	v_mov_b64 v[58:59], 0
	v_mov_b64 v[60:61], 0
	v_mov_b64 v[50:51], 0
	v_mov_b64 v[52:53], 0
	v_mov_b64 v[42:43], 0
	v_mov_b64 v[44:45], 0
	v_mov_b64 v[34:35], 0
	v_mov_b64 v[36:37], 0
	v_mov_b64 v[26:27], 0
	v_mov_b64 v[28:29], 0
	v_mov_b64 v[18:19], 0
	v_mov_b64 v[20:21], 0
	v_mov_b64 v[10:11], 0
	v_mov_b64 v[12:13], 0
	v_mov_b64 v[2:3], 0
	v_mov_b64 v[4:5], 0
	v_mov_b64 v[62:63], 0
	v_mov_b64 v[64:65], 0
	v_mov_b64 v[54:55], 0
	v_mov_b64 v[56:57], 0
	v_mov_b64 v[46:47], 0
	v_mov_b64 v[48:49], 0
	v_mov_b64 v[38:39], 0
	v_mov_b64 v[40:41], 0
	v_mov_b64 v[30:31], 0
	v_mov_b64 v[32:33], 0
	v_mov_b64 v[22:23], 0
	v_mov_b64 v[24:25], 0
	v_mov_b64 v[14:15], 0
	v_mov_b64 v[16:17], 0
	v_mov_b64 v[6:7], 0
	v_mov_b64 v[8:9], 0
	s_cbranch_vccnz .LBB0_601
	s_barrier
	s_branch .LBB0_601
